# sparse-attention claim handoff waits for the outstanding claim only when it has not returned yet (sentinel) instead of draining all stores
# baseline (speedup 1.0000x reference)
; __device__ void phase_y(const Params& p, int layer, unsigned char* smem) {
;   constexpr int NI = 8 * 2 * 64;
;   const int G = gridDim.x;
;   for (int i = blockIdx.x; i < NI / 2; i += G) {
; #pragma unroll 1
;     for (int h = 0; h < 2; ++h) {
;       int it = h ? (NI - 1 - i) : i;
;       int qt = 63 - (it >> 4); int r = it & 15; int b = r >> 1, g = r & 1;
;       item_nsa(p, layer, b, g, qt, smem);
;     }
;   }
.LBB0_27:
	v_writelane_b32 v255, s52, 19
	s_add_i32 s0, s52, -1
	s_mul_hi_i32 s1, s0, 0x66666667
	s_lshr_b32 s6, s1, 31
	s_ashr_i32 s1, s1, 1
	s_add_i32 s8, s1, s6
	v_writelane_b32 v255, s53, 20
	s_mov_b32 s6, s8
	s_mul_i32 s1, s8, 5
	v_writelane_b32 v255, s6, 21
	s_sub_i32 s44, s0, s1
	s_mov_b64 s[0:1], -1
	v_writelane_b32 v255, s7, 22
	s_cmp_lt_i32 s44, 2
	s_mov_b64 s[70:71], 0
	s_cbranch_scc1 .LBB0_281
	s_cmp_gt_i32 s44, 2
	v_writelane_b32 v255, s44, 23
	s_cbranch_scc0 .LBB0_192
	s_cmp_eq_u32 s44, 3
	s_mov_b64 s[70:71], -1
	s_cbranch_scc0 .LBB0_191
	v_readlane_b32 s0, v254, 2
	v_readlane_b32 s1, v254, 3
	s_andn2_b64 vcc, exec, s[0:1]
	s_cbranch_vccnz .LBB0_190
	v_readlane_b32 s9, v253, 0
	v_writelane_b32 v255, s87, 62
	v_readlane_b32 s0, v255, 60
	s_cmp_lg_u32 s0, 1
	s_cbranch_scc1 .LBB0_33
	s_mov_b32 s0, 1
	v_writelane_b32 v255, s0, 62
	s_and_b32 s0, s9, 7
	s_lshl_b32 s0, s0, 6
	v_readlane_b32 s1, v255, 21
	s_lshl_b32 s1, s1, 2
	s_add_i32 s0, s0, s1
	s_addk_i32 s0, 0x3600
	s_add_u32 s30, s88, s0
	s_addc_u32 s31, s89, 0
	v_writelane_b32 v255, s30, 54
	v_writelane_b32 v255, s31, 55
	v_cmp_eq_u32_e32 vcc, 0, v210
	s_and_saveexec_b64 s[38:39], vcc
	v_mov_b32_e32 v211, -1
	v_mov_b32_e32 v2, 1
	s_nop 4
	global_atomic_add v211, v1, v2, s[30:31] sc0
	s_or_b64 exec, exec, s[38:39]
	s_branch .LBB0_33

; __device__ void phase_y(const Params& p, int layer, unsigned char* smem) {
;     ...
;   for (int i = blockIdx.x; i < NI / 2; i += G) {
; #pragma unroll 1
;     for (int h = 0; h < 2; ++h) {
;       int it = h ? (NI - 1 - i) : i;
;       int qt = 63 - (it >> 4); int r = it & 15; int b = r >> 1, g = r & 1;
;       item_nsa(p, layer, b, g, qt, smem);
;     }
.Lnsa_next:
	v_cmp_eq_u32_e32 vcc, 0, v210
	s_and_saveexec_b64 s[38:39], vcc
	s_cbranch_execz .Lnsa_n1
	v_cmp_eq_u32_e32 vcc, -1, v211
	s_cbranch_vccz .Lnsa_rdy
	s_waitcnt vmcnt(0)
.Lnsa_rdy:
	v_mov_b32_e32 v0, 0x13110
	ds_write_b32 v0, v211
	v_readlane_b32 s30, v255, 54
	v_readlane_b32 s31, v255, 55
	v_mov_b32_e32 v2, 1
	s_waitcnt lgkmcnt(0)
	v_mov_b32_e32 v211, -1
	s_nop 4
	global_atomic_add v211, v1, v2, s[30:31] sc0
